# c17 + pass C unit end no longer drains the Mix stores (no loads are outstanding there once the touch is gone)
# baseline (speedup 1.0000x reference)
.LBB0_1112:
	s_cmpk_lt_i32 s67, 0x110
	s_mov_b32 s30, s67
	s_barrier
	s_cbranch_scc0 .LBB0_1233

.LBB0_1298:
	s_andn2_b64 vcc, exec, s[4:5]
	s_mov_b32 s42, s71
	s_barrier
	s_cbranch_vccz .LBB0_1400
